# tile-loop headers scalarised for the fixed shapes: 32-bit s_mul/s_cmpk/s_cselect_b64 next-tile test (4 headers), s_not_b64 mask complement (3), dead not-divisible-by-8 branch pairs removed (8 sites)
# speedup vs baseline: 1.0015x; 1.0015x over previous
; #define INP(i) ((const float*)ldp(T, (i)))
;     __device__ bool next(int i, Unit& u) const {
;         const long L = (long)i * G + c; if (L >= nwg) return false;
;         int wgid = (int)L; { const int q = nwg / NXCD, r = nwg % NXCD, xcd = wgid % NXCD, off = wgid / NXCD; wgid = (xcd < r ? xcd * (q + 1) : r * (q + 1) + (xcd - r) * q) + off; }
;         const int nig = WGM * nN, gid = wgid / nig, fm = gid * WGM, gsz = (nM - fm) < WGM ? (nM - fm) : WGM;
;         u.pm = fm + ((wgid % nig) % gsz); u.pn = (wgid % nig) / gsz; return true;
;     }
; __global__ void __launch_bounds__(NTHR, 2) fwd_megakernel(Args P) {
;     ...
;             const bool dn = s == 6;
;             const bf16_t* Am = dn ? H : kind == 2 ? T1 + CHUNK_ADJ : T2;
;             const bf16_t* Wm = Wb + (dn ? WO_F_D0 + (size_t)L * WO_F_STRIDE : kind == 0 ? WO_A_OUT0 + (size_t)a * WO_A_STRIDE : kind == 1 ? WO_B_OUT : WO_C_OUT);
;             pg8::Gemm g{Am, Wm, M, D, dn ? FH : D, dn ? FH : D, 0, (!dn && kind == 2) ? 2u * CHUNK_ADJ : 0u}; S.init(M, D, G, bidx);
;             if (dn && L == DEPTH - 1 && teams) { pg8::EpiResFin E{XB, ss_next, OUTP, INP(3), (unsigned*)(ws + WS_BAR) + XL_PCNT, lds}; pg8::gemm_phase<pg8::EpiResFin, true>(lds, g, S, E); }
;             else { pg8::EpiRes E{XB, dn ? ss_next : ss_ffn, lds}; pg8::gemm_phase<pg8::EpiRes, true>(lds, g, S, E); }
.LBB0_127:
	s_add_u32 s4, s20, 0x800000
	s_addc_u32 s5, s21, 0
	s_cmp_eq_u32 s86, 2
	v_readlane_b32 s8, v254, 54
	s_cselect_b32 s8, s4, s8
	v_readlane_b32 s4, v254, 55
	s_cselect_b32 s9, s5, s4
	s_and_b64 s[4:5], s[0:1], exec
	s_cselect_b32 s4, s11, s9
	v_writelane_b32 v254, s4, 59
	s_cselect_b32 s4, s10, s8
	v_writelane_b32 v254, s4, 60
	s_lshl_b64 s[4:5], s[6:7], 19
	s_add_u32 s4, s14, s4
	s_addc_u32 s5, s15, s5
	s_add_u32 s4, s4, 0x100000
	s_addc_u32 s5, s5, 0
	v_writelane_b32 v254, s4, 62
	s_nop 1
	v_writelane_b32 v254, s5, 63
	s_lshl_b64 s[4:5], s[34:35], 1
	v_readlane_b32 s6, v254, 29
	s_add_u32 s4, s6, s4
	v_writelane_b32 v254, s4, 46
	s_nop 0
	v_readlane_b32 s4, v254, 30
	s_addc_u32 s4, s4, s5
	s_cmp_lg_u32 s86, 2
	v_writelane_b32 v254, s4, 44
	s_cselect_b64 s[4:5], -1, 0
	s_or_b64 s[4:5], s[0:1], s[4:5]
	s_and_b64 s[4:5], s[4:5], exec
	s_cselect_b32 s4, 0, 0x800000
	v_writelane_b32 v254, s4, 48
	s_sub_i32 s4, s41, 22
	s_cmp_lt_u32 s4, 7
	s_cselect_b64 s[4:5], -1, 0
	s_and_b64 s[4:5], s[0:1], s[4:5]
	v_readlane_b32 s6, v254, 23
	s_cmp_lg_u32 s6, 0
	s_cselect_b64 s[6:7], -1, 0
	s_and_b64 s[4:5], s[4:5], s[6:7]
	s_andn2_b64 vcc, exec, s[4:5]
	s_mov_b64 s[4:5], -1
	s_cbranch_vccz .LBB0_177
	v_mov_b32_e32 v4, v220
	s_cmpk_lt_i32 s16, 0x200
	s_cselect_b64 s[6:7], -1, 0
	s_cmpk_gt_i32 s16, 0x1ff
	v_readfirstlane_b32 s8, v4
	s_cbranch_scc1 .LBB0_134
	s_ashr_i32 s4, s16, 31
	s_lshr_b32 s4, s4, 29
	s_add_i32 s9, s16, s4
	s_and_b32 s4, s9, -8
	s_sub_i32 s14, s16, s4
	s_lshl_b32 s15, s14, 6
	s_ashr_i32 s4, s9, 3
	s_add_i32 s4, s15, s4
	s_ashr_i32 s5, s4, 31
	s_lshr_b32 s5, s5, 27
	s_add_i32 s5, s4, s5
	s_ashr_i32 s9, s5, 5
	s_and_b32 s5, s5, 0xffe0
	s_sub_i32 s4, s4, s5
	s_bfe_i32 s5, s4, 0x80000
	s_bfe_u32 s5, s5, 0x3000c
	s_add_i32 s5, s4, s5
	s_bfe_i32 s14, s5, 0x80000
	s_and_b32 s5, s5, 0xf8
	s_sub_i32 s4, s4, s5
	s_lshl_b32 s9, s9, 3
	s_sext_i32_i16 s14, s14
	s_sext_i32_i8 s4, s4
	s_add_i32 s35, s9, s4
	s_ashr_i32 s34, s14, 3

;     __device__ bool next(int i, Unit& u) const {
;         const long L = (long)i * G + c; if (L >= nwg) return false;
;         int wgid = (int)L; { const int q = nwg / NXCD, r = nwg % NXCD, xcd = wgid % NXCD, off = wgid / NXCD; wgid = (xcd < r ? xcd * (q + 1) : r * (q + 1) + (xcd - r) * q) + off; }
;         const int nig = WGM * nN, gid = wgid / nig, fm = gid * WGM, gsz = (nM - fm) < WGM ? (nM - fm) : WGM;
;         u.pm = fm + ((wgid % nig) % gsz); u.pn = (wgid % nig) / gsz; return true;
; template <class Epi, bool ALIGN_EPI>
; __device__ __forceinline__ void gemm_phase(LAS unsigned char* lds, const Gemm g, const StaticOrder& S, const Epi& E) {
;     ...
;         const bool has_next = S.next(ui + 1, nxt);
;         const char* nA = has_next ? (const char*)g.A + (size_t)nxt.pm * tstepA + (size_t)nxt.pn * g.a_pn_off * 2 + (size_t)(nxt.pm >> 4) * g.a_adj : cA; const char* nB = has_next ? (const char*)g.Bt + (size_t)nxt.pn * tstepB : cB;
.LBB0_140:
	v_add_u32_e32 v132, 0x10000, v244
	v_add_u32_e32 v152, 0x14000, v244
	ds_read_b128 v[108:111], v132
	ds_read_b128 v[120:123], v132 offset:1024
	ds_read_b128 v[128:131], v132 offset:2048
	ds_read_b128 v[132:135], v132 offset:3072
	ds_read_b128 v[136:139], v152
	ds_read_b128 v[144:147], v152 offset:1024
	ds_read_b128 v[148:151], v152 offset:2048
	ds_read_b128 v[152:155], v152 offset:3072
	ds_read_b128 v[156:159], v245
	ds_read_b128 v[160:163], v245 offset:1024
	ds_read_b128 v[164:167], v245 offset:2048
	ds_read_b128 v[176:179], v245 offset:3072
	ds_read_b128 v[180:183], v245 offset:4096
	ds_read_b128 v[184:187], v245 offset:5120
	ds_read_b128 v[188:191], v245 offset:6144
	ds_read_b128 v[202:205], v245 offset:7168
	s_add_i32 s80, s80, 1
	s_mul_i32 s0, s80, s87
	s_add_i32 s4, s0, s16
	s_cmpk_lt_u32 s4, 0x200
	s_cselect_b64 s[0:1], -1, 0
	s_cbranch_scc0 .LBB0_146
	s_ashr_i32 s5, s4, 31
	s_lshr_b32 s5, s5, 29
	s_add_i32 s8, s4, s5
	s_and_b32 s5, s8, -8
	s_sub_i32 s9, s4, s5
	s_lshl_b32 s14, s9, 6
	s_ashr_i32 s4, s8, 3
	s_add_i32 s4, s14, s4
	s_ashr_i32 s5, s4, 31
	s_lshr_b32 s5, s5, 27
	s_add_i32 s5, s4, s5
	s_ashr_i32 s8, s5, 5
	s_lshl_b32 s8, s8, 3
	s_sub_i32 s9, 0x80, s8
	s_min_i32 s9, s9, 8
	s_abs_i32 s14, s9
	s_andn2_b32 s5, s5, 31
	s_sub_i32 s4, s4, s5
	s_lshr_b32 s14, s4, 3
	s_and_b32 s4, s4, 7
	s_add_i32 s36, s8, s4
.LBB0_146:
	s_not_b64 s[8:9], s[0:1]
	s_andn2_b64 vcc, exec, s[0:1]
	s_mov_b64 s[0:1], s[54:55]
	s_cbranch_vccnz .LBB0_148
	s_mul_i32 s1, s17, s36
	v_readlane_b32 s4, v254, 60
	s_mul_hi_i32 s0, s17, s36
	s_add_u32 s1, s4, s1
	v_readlane_b32 s4, v254, 59
	s_addc_u32 s4, s4, s0
	s_ashr_i32 s0, s36, 4
	v_readlane_b32 s37, v254, 48
	s_mul_hi_i32 s5, s0, s37
	s_mul_i32 s0, s0, s37
	s_add_u32 s0, s1, s0
	s_addc_u32 s1, s4, s5

; #define INP(i) ((const float*)ldp(T, (i)))
;     __device__ bool next(int i, Unit& u) const {
;         const long L = (long)i * G + c; if (L >= nwg) return false;
;         int wgid = (int)L; { const int q = nwg / NXCD, r = nwg % NXCD, xcd = wgid % NXCD, off = wgid / NXCD; wgid = (xcd < r ? xcd * (q + 1) : r * (q + 1) + (xcd - r) * q) + off; }
;         const int nig = WGM * nN, gid = wgid / nig, fm = gid * WGM, gsz = (nM - fm) < WGM ? (nM - fm) : WGM;
;         u.pm = fm + ((wgid % nig) % gsz); u.pn = (wgid % nig) / gsz; return true;
;     }
; __global__ void __launch_bounds__(NTHR, 2) fwd_megakernel(Args P) {
;     ...
;             if (dn && L == DEPTH - 1 && teams) { pg8::EpiResFin E{XB, ss_next, OUTP, INP(3), (unsigned*)(ws + WS_BAR) + XL_PCNT, lds}; pg8::gemm_phase<pg8::EpiResFin, true>(lds, g, S, E); }
;             else { pg8::EpiRes E{XB, dn ? ss_next : ss_ffn, lds}; pg8::gemm_phase<pg8::EpiRes, true>(lds, g, S, E); }
.LBB0_177:
	s_and_b64 vcc, exec, s[4:5]
	s_cbranch_vccz .LBB0_242
	v_readlane_b32 s0, v254, 9
	v_readfirstlane_b32 s35, v3
	v_readfirstlane_b32 s34, v2
	v_mov_b32_e32 v0, s0
	ds_read_b64 v[2:3], v0
	s_cmpk_lt_i32 s16, 0x200
	s_waitcnt lgkmcnt(0)
	v_readfirstlane_b32 s1, v3
	v_readfirstlane_b32 s0, v2
	v_mov_b32_e32 v2, v220
	s_nop 0
	v_writelane_b32 v255, s0, 0
	v_readfirstlane_b32 s6, v2
	s_nop 0
	v_writelane_b32 v255, s1, 1
	s_cselect_b64 s[0:1], -1, 0
	s_cmpk_gt_i32 s16, 0x1ff
	s_cbranch_scc1 .LBB0_184
	s_ashr_i32 s4, s16, 31
	s_lshr_b32 s4, s4, 29
	s_add_i32 s7, s16, s4
	s_and_b32 s4, s7, -8
	s_sub_i32 s8, s16, s4
	s_lshl_b32 s9, s8, 6
	s_ashr_i32 s4, s7, 3
	s_add_i32 s4, s9, s4
	s_ashr_i32 s5, s4, 31
	s_lshr_b32 s5, s5, 27
	s_add_i32 s5, s4, s5
	s_ashr_i32 s7, s5, 5
	s_andn2_b32 s5, s5, 31
	s_sub_i32 s4, s4, s5
	s_bfe_i32 s5, s4, 0x80000
	s_bfe_u32 s5, s5, 0x3000c
	s_add_i32 s5, s4, s5
	s_bfe_i32 s8, s5, 0x80000
	s_and_b32 s5, s5, 0xf8
	s_sub_i32 s4, s4, s5
	s_lshl_b32 s7, s7, 3
	s_sext_i32_i16 s8, s8
	s_sext_i32_i8 s4, s4
	s_add_i32 s14, s7, s4
	s_ashr_i32 s96, s8, 3

;     __device__ bool next(int i, Unit& u) const {
;         const long L = (long)i * G + c; if (L >= nwg) return false;
;         int wgid = (int)L; { const int q = nwg / NXCD, r = nwg % NXCD, xcd = wgid % NXCD, off = wgid / NXCD; wgid = (xcd < r ? xcd * (q + 1) : r * (q + 1) + (xcd - r) * q) + off; }
;         const int nig = WGM * nN, gid = wgid / nig, fm = gid * WGM, gsz = (nM - fm) < WGM ? (nM - fm) : WGM;
;         u.pm = fm + ((wgid % nig) % gsz); u.pn = (wgid % nig) / gsz; return true;
; template <class Epi, bool ALIGN_EPI>
; __device__ __forceinline__ void gemm_phase(LAS unsigned char* lds, const Gemm g, const StaticOrder& S, const Epi& E) {
;     ...
;         const bool has_next = S.next(ui + 1, nxt);
;         const char* nA = has_next ? (const char*)g.A + (size_t)nxt.pm * tstepA + (size_t)nxt.pn * g.a_pn_off * 2 + (size_t)(nxt.pm >> 4) * g.a_adj : cA; const char* nB = has_next ? (const char*)g.Bt + (size_t)nxt.pn * tstepB : cB;
.LBB0_190:
	v_add_u32_e32 v142, 0x10000, v245
	v_add_u32_e32 v158, 0x14000, v245
	ds_read_b128 v[130:133], v142
	ds_read_b128 v[134:137], v142 offset:1024
	ds_read_b128 v[138:141], v142 offset:2048
	ds_read_b128 v[142:145], v142 offset:3072
	ds_read_b128 v[146:149], v158
	ds_read_b128 v[150:153], v158 offset:1024
	ds_read_b128 v[154:157], v158 offset:2048
	ds_read_b128 v[158:161], v158 offset:3072
	ds_read_b128 v[162:165], v246
	ds_read_b128 v[166:169], v246 offset:1024
	ds_read_b128 v[170:173], v246 offset:2048
	ds_read_b128 v[174:177], v246 offset:3072
	ds_read_b128 v[178:181], v246 offset:4096
	ds_read_b128 v[182:185], v246 offset:5120
	ds_read_b128 v[186:189], v246 offset:6144
	ds_read_b128 v[190:193], v246 offset:7168
	s_add_i32 s39, s39, 1
	s_mul_i32 s0, s39, s87
	v_readlane_b32 s4, v255, 8
	s_add_i32 s4, s0, s4
	s_cmpk_lt_u32 s4, 0x200
	s_cselect_b64 s[0:1], -1, 0
	s_cbranch_scc0 .LBB0_196
	s_ashr_i32 s5, s4, 31
	s_lshr_b32 s5, s5, 29
	s_add_i32 s8, s4, s5
	s_and_b32 s5, s8, -8
	s_sub_i32 s9, s4, s5
	s_lshl_b32 s15, s9, 6
	s_ashr_i32 s4, s8, 3
	s_add_i32 s4, s15, s4
	s_ashr_i32 s5, s4, 31
	s_lshr_b32 s5, s5, 27
	s_add_i32 s5, s4, s5
	s_ashr_i32 s8, s5, 5
	s_lshl_b32 s8, s8, 3
	s_sub_i32 s9, 0x80, s8
	s_min_i32 s9, s9, 8
	s_abs_i32 s15, s9
	s_andn2_b32 s5, s5, 31
	s_sub_i32 s4, s4, s5
	s_lshr_b32 s80, s4, 3
	s_and_b32 s4, s4, 7
	s_add_i32 s50, s8, s4
.LBB0_196:
	s_not_b64 s[8:9], s[0:1]
	s_andn2_b64 vcc, exec, s[0:1]
	s_mov_b64 s[0:1], s[54:55]
	s_cbranch_vccnz .LBB0_198
	s_mul_i32 s1, s78, s50
	v_readlane_b32 s4, v254, 60
	s_mul_hi_i32 s0, s78, s50
	s_add_u32 s1, s4, s1
	v_readlane_b32 s4, v254, 59
	s_addc_u32 s4, s4, s0
	s_ashr_i32 s0, s50, 4
	v_readlane_b32 s15, v254, 48
	s_mul_hi_i32 s5, s0, s15
	s_mul_i32 s0, s0, s15
	s_add_u32 s0, s1, s0
	s_addc_u32 s1, s4, s5

; #define INP(i) ((const float*)ldp(T, (i)))
;     __device__ bool next(int i, Unit& u) const {
;         const long L = (long)i * G + c; if (L >= nwg) return false;
;         int wgid = (int)L; { const int q = nwg / NXCD, r = nwg % NXCD, xcd = wgid % NXCD, off = wgid / NXCD; wgid = (xcd < r ? xcd * (q + 1) : r * (q + 1) + (xcd - r) * q) + off; }
;         const int nig = WGM * nN, gid = wgid / nig, fm = gid * WGM, gsz = (nM - fm) < WGM ? (nM - fm) : WGM;
;         u.pm = fm + ((wgid % nig) % gsz); u.pn = (wgid % nig) / gsz; return true;
;     }
; __global__ void __launch_bounds__(NTHR, 2) fwd_megakernel(Args P) {
;     ...
;             pg8::EpiPair E{ffn ? H : T1, ffn ? FH : D, ffn ? ss_ffn : ss_mix, ffn ? 1 : 0, ffn ? 0u : CHUNK_ADJ}; pg8::gemm_phase<pg8::EpiPair, true>(lds, g, S, E);
;         } else if (s == 0 || s == 1 || s == 3) {
;             const bool grp = s == 3;
;             pg8::Gemm g{grp ? T2 : XB, Wb + (grp ? WO_C_GRP : s == 1 ? WO_B_B : WO_C_IN), M, D, grp ? 256 : D, D, grp ? 256 : 0, 0u}; S.init(M, D, G, bidx);
;             pg8::EpiPlain E{s == 0 ? T1 : T1 + CHUNK_ADJ, D, grp ? nullptr : ss_mix, grp ? INP(14) : nullptr, CHUNK_ADJ}; pg8::gemm_phase<pg8::EpiPlain, true>(lds, g, S, E);
.LBB0_248:
	v_mov_b32_e32 v0, v220
	s_cmpk_lt_i32 s16, 0x200
	s_cselect_b64 s[36:37], -1, 0
	s_cmpk_gt_i32 s16, 0x1ff
	v_readfirstlane_b32 s7, v0
	s_cbranch_scc1 .LBB0_254
	s_ashr_i32 s4, s16, 31
	s_lshr_b32 s4, s4, 29
	s_add_i32 s14, s16, s4
	s_and_b32 s4, s14, -8
	s_sub_i32 s15, s16, s4
	s_lshl_b32 s17, s15, 6
	s_ashr_i32 s4, s14, 3
	s_add_i32 s4, s17, s4
	s_ashr_i32 s5, s4, 31
	s_lshr_b32 s5, s5, 27
	s_add_i32 s5, s4, s5
	s_ashr_i32 s14, s5, 5
	s_andn2_b32 s5, s5, 31
	s_sub_i32 s4, s4, s5
	s_bfe_i32 s5, s4, 0x80000
	s_bfe_u32 s5, s5, 0x3000c
	s_add_i32 s5, s4, s5
	s_bfe_i32 s15, s5, 0x80000
	s_and_b32 s5, s5, 0xf8
	s_sub_i32 s4, s4, s5
	s_lshl_b32 s14, s14, 3
	s_sext_i32_i16 s15, s15
	s_sext_i32_i8 s4, s4
	s_add_i32 s94, s14, s4
	s_ashr_i32 s51, s15, 3

;     __device__ bool next(int i, Unit& u) const {
;         const long L = (long)i * G + c; if (L >= nwg) return false;
;         int wgid = (int)L; { const int q = nwg / NXCD, r = nwg % NXCD, xcd = wgid % NXCD, off = wgid / NXCD; wgid = (xcd < r ? xcd * (q + 1) : r * (q + 1) + (xcd - r) * q) + off; }
;         const int nig = WGM * nN, gid = wgid / nig, fm = gid * WGM, gsz = (nM - fm) < WGM ? (nM - fm) : WGM;
;         u.pm = fm + ((wgid % nig) % gsz); u.pn = (wgid % nig) / gsz; return true;
; template <class Epi, bool ALIGN_EPI>
; __device__ __forceinline__ void gemm_phase(LAS unsigned char* lds, const Gemm g, const StaticOrder& S, const Epi& E) {
;     ...
;         const bool has_next = S.next(ui + 1, nxt);
;         const char* nA = has_next ? (const char*)g.A + (size_t)nxt.pm * tstepA + (size_t)nxt.pn * g.a_pn_off * 2 + (size_t)(nxt.pm >> 4) * g.a_adj : cA; const char* nB = has_next ? (const char*)g.Bt + (size_t)nxt.pn * tstepB : cB;
.LBB0_260:
	v_add_u32_e32 v0, 0x10000, v179
	ds_read_b128 v[130:133], v0
	ds_read_b128 v[134:137], v0 offset:1024
	ds_read_b128 v[138:141], v0 offset:2048
	ds_read_b128 v[142:145], v0 offset:3072
	v_add_u32_e32 v0, 0x14000, v179
	ds_read_b128 v[146:149], v0
	ds_read_b128 v[150:153], v0 offset:1024
	ds_read_b128 v[154:157], v0 offset:2048
	ds_read_b128 v[158:161], v0 offset:3072
	ds_read_b128 v[182:185], v180
	ds_read_b128 v[186:189], v180 offset:1024
	ds_read_b128 v[190:193], v180 offset:2048
	ds_read_b128 v[202:205], v180 offset:3072
	ds_read_b128 v[206:209], v180 offset:4096
	ds_read_b128 v[210:213], v180 offset:5120
	ds_read_b128 v[214:217], v180 offset:6144
	ds_read_b128 v[240:243], v180 offset:7168
	s_add_i32 s85, s85, 1
	s_mul_i32 s0, s85, s87
	s_add_i32 s4, s0, s16
	s_cmpk_lt_u32 s4, 0x200
	s_cselect_b64 s[0:1], -1, 0
	s_cbranch_scc0 .LBB0_266
	s_ashr_i32 s5, s4, 31
	s_lshr_b32 s5, s5, 29
	s_add_i32 s6, s4, s5
	s_and_b32 s5, s6, -8
	s_sub_i32 s7, s4, s5
	s_lshl_b32 s39, s7, 6
	s_ashr_i32 s4, s6, 3
	s_add_i32 s4, s39, s4
	s_ashr_i32 s5, s4, 31
	s_lshr_b32 s5, s5, 27
	s_add_i32 s5, s4, s5
	s_ashr_i32 s6, s5, 5
	s_lshl_b32 s6, s6, 3
	s_sub_i32 s7, 0x80, s6
	s_min_i32 s7, s7, 8
	s_abs_i32 s39, s7
	s_andn2_b32 s5, s5, 31
	s_sub_i32 s4, s4, s5
	s_lshr_b32 s39, s4, 3
	s_and_b32 s4, s4, 7
	s_add_i32 s54, s6, s4
.LBB0_266:
	s_not_b64 s[6:7], s[0:1]
	s_andn2_b64 vcc, exec, s[0:1]
	s_mov_b64 s[96:97], s[58:59]
	s_cbranch_vccnz .LBB0_268
	s_ashr_i32 s55, s54, 31
	s_lshl_b64 s[0:1], s[54:55], 19
	v_readlane_b32 s4, v254, 59
	s_add_u32 s0, s4, s0
	v_readlane_b32 s4, v254, 48
	v_readlane_b32 s5, v254, 49
	s_mov_b32 s44, s4
	s_addc_u32 s1, s75, s1
	s_mul_i32 s5, s44, s39
	s_mul_hi_i32 s4, s4, s39
	s_add_u32 s96, s0, s5
	s_addc_u32 s97, s1, s4

;     __device__ bool next(int i, Unit& u) const {
;         const long L = (long)i * G + c; if (L >= nwg) return false;
;         int wgid = (int)L; { const int q = nwg / NXCD, r = nwg % NXCD, xcd = wgid % NXCD, off = wgid / NXCD; wgid = (xcd < r ? xcd * (q + 1) : r * (q + 1) + (xcd - r) * q) + off; }
;         const int nig = WGM * nN, gid = wgid / nig, fm = gid * WGM, gsz = (nM - fm) < WGM ? (nM - fm) : WGM;
;         u.pm = fm + ((wgid % nig) % gsz); u.pn = (wgid % nig) / gsz; return true;
;     }
; __global__ void __launch_bounds__(NTHR, 2) fwd_megakernel(Args P) {
;     ...
;         if (s == 0 && kind == 0) {
;             pg8::Gemm g{XB, Wb + WO_A_IN0 + (size_t)a * WO_A_STRIDE, M, 2048, D, D, 0, 0u}; S.init(M, 2048, G, bidx);
;             pg8::EpiGeluStats E{T1, 2048, ss_mix, (float*)(ws + WS_VST + (size_t)a * MiB), lds}; pg8::gemm_phase<pg8::EpiGeluStats, true>(lds, g, S, E);
.LBB0_330:
	v_mov_b32_e32 v0, v220
	s_cmpk_lt_i32 s16, 0x400
	s_cselect_b64 s[0:1], -1, 0
	s_cmpk_gt_i32 s16, 0x3ff
	v_readfirstlane_b32 s6, v0
	s_cbranch_scc1 .LBB0_336
	s_ashr_i32 s4, s16, 31
	s_lshr_b32 s4, s4, 29
	s_add_i32 s7, s16, s4
	s_and_b32 s4, s7, -8
	s_sub_i32 s8, s16, s4
	s_lshl_b32 s9, s8, 7
	s_ashr_i32 s4, s7, 3
	s_add_i32 s4, s9, s4
	s_ashr_i32 s5, s4, 31
	s_lshr_b32 s5, s5, 26
	s_add_i32 s5, s4, s5
	s_ashr_i32 s7, s5, 6
	s_andn2_b32 s5, s5, 63
	s_sub_i32 s4, s4, s5
	s_bfe_i32 s5, s4, 0x80000
	s_bfe_u32 s5, s5, 0x3000c
	s_add_i32 s5, s4, s5
	s_bfe_i32 s8, s5, 0x80000
	s_and_b32 s5, s5, 0xf8
	s_sub_i32 s4, s4, s5
	s_lshl_b32 s7, s7, 3
	s_sext_i32_i16 s8, s8
	s_sext_i32_i8 s4, s4
	s_add_i32 s10, s7, s4
	s_ashr_i32 s46, s8, 3

; #define PG8_STAGE(bufoff, gbase, voff) do { _Pragma("unroll") for (int _i = 0; _i < 2; ++_i) { \
;         const unsigned _m0 = ldsb + (unsigned)((bufoff) + _i * 8192); const char* _gb = (const char*)(gbase); \
;         asm volatile("s_mov_b32 m0, %0\n\ts_nop 0\n\tglobal_load_lds_dwordx4 %1, %2" :: "s"(_m0), "v"((voff)[_i]), "s"(_gb) : "m0", "memory"); } } while (0)
; #define PG8_LDA(dst, b, h) do { _Pragma("unroll") for (int m = 0; m < 4; ++m) _Pragma("unroll") for (int k = 0; k < 2; ++k) dst[m][k] = *(const LAS bf16x8*)(lds + PG8_SA(b, h) + aoff + m * 2048 + k * 1024); } while (0)
; #define PG8_LDB(dst, b, h) do { _Pragma("unroll") for (int n = 0; n < 2; ++n) _Pragma("unroll") for (int k = 0; k < 2; ++k) dst[n][k] = *(const LAS bf16x8*)(lds + PG8_SB(b, h) + boff + n * 2048 + k * 1024); } while (0)
; #define PG8_SCHED __builtin_amdgcn_sched_barrier(0)
;     __device__ bool next(int i, Unit& u) const {
;         const long L = (long)i * G + c; if (L >= nwg) return false;
;         int wgid = (int)L; { const int q = nwg / NXCD, r = nwg % NXCD, xcd = wgid % NXCD, off = wgid / NXCD; wgid = (xcd < r ? xcd * (q + 1) : r * (q + 1) + (xcd - r) * q) + off; }
;         const int nig = WGM * nN, gid = wgid / nig, fm = gid * WGM, gsz = (nM - fm) < WGM ? (nM - fm) : WGM;
;         u.pm = fm + ((wgid % nig) % gsz); u.pn = (wgid % nig) / gsz; return true;
; template <class Epi, bool ALIGN_EPI>
; __device__ __forceinline__ void gemm_phase(LAS unsigned char* lds, const Gemm g, const StaticOrder& S, const Epi& E) {
;     ...
;         const bool has_next = S.next(ui + 1, nxt);
;         const char* nA = has_next ? (const char*)g.A + (size_t)nxt.pm * tstepA + (size_t)nxt.pn * g.a_pn_off * 2 + (size_t)(nxt.pm >> 4) * g.a_adj : cA; const char* nB = has_next ? (const char*)g.Bt + (size_t)nxt.pn * tstepB : cB;
;         for (int t = 0; t < nt; t += 2) {
;             const bool last = (t == nt - 2);
;             const char* a1 = cA + (size_t)(t + 1) * kstep;
;             const char* a2 = last ? nA : cA + (size_t)(t + 2) * kstep; const char* b2 = last ? nB : cB + (size_t)(t + 2) * kstep;
;             const char* a3 = a2 + kstep; const char* b3 = b2 + kstep;
;             PG8_LDB(B0, 0, 0); PG8_LDB(B1, 0, 1); PG8_SCHED; PG8_LDA(At, 0, 0); PG8_STAGE(PG8_SA(1, 1), a1 + hstepA, voffA);
.LBB0_342:
	v_add_u32_e32 v0, 0x10000, v187
	ds_read_b128 v[34:37], v0
	ds_read_b128 v[54:57], v0 offset:1024
	ds_read_b128 v[74:77], v0 offset:2048
	ds_read_b128 v[94:97], v0 offset:3072
	v_add_u32_e32 v0, 0x14000, v187
	ds_read_b128 v[110:113], v0
	ds_read_b128 v[126:129], v0 offset:1024
	ds_read_b128 v[146:149], v0 offset:2048
	ds_read_b128 v[160:163], v0 offset:3072
	ds_read_b128 v[164:167], v188
	ds_read_b128 v[168:171], v188 offset:1024
	ds_read_b128 v[172:175], v188 offset:2048
	ds_read_b128 v[176:179], v188 offset:3072
	ds_read_b128 v[190:193], v188 offset:4096
	ds_read_b128 v[202:205], v188 offset:5120
	ds_read_b128 v[206:209], v188 offset:6144
	ds_read_b128 v[210:213], v188 offset:7168
	s_add_i32 s92, s92, 1
	s_mul_i32 s4, s92, s87
	s_add_i32 s4, s4, s16
	s_cmpk_lt_u32 s4, 0x400
	s_cselect_b64 s[8:9], -1, 0
	s_cbranch_scc0 .LBB0_348
	s_ashr_i32 s5, s4, 31
	s_lshr_b32 s5, s5, 29
	s_add_i32 s11, s4, s5
	s_and_b32 s5, s11, -8
	s_sub_i32 s26, s4, s5
	s_lshl_b32 s27, s26, 7
	s_ashr_i32 s4, s11, 3
	s_add_i32 s4, s27, s4
	s_ashr_i32 s5, s4, 31
	s_lshr_b32 s5, s5, 26
	s_add_i32 s5, s4, s5
	s_ashr_i32 s11, s5, 6
	s_lshl_b32 s11, s11, 3
	s_sub_i32 s26, 0x80, s11
	s_min_i32 s27, s26, 8
	s_abs_i32 s26, s27
	s_andn2_b32 s5, s5, 63
	s_sub_i32 s4, s4, s5
	s_lshr_b32 s26, s4, 3
	s_and_b32 s4, s4, 7
	s_add_i32 s28, s11, s4
